# v17
# baseline (speedup 1.0000x reference)
; #define WAIT_L(n) asm volatile("s_waitcnt lgkmcnt(%0)" ::"n"(n) : "memory")
; #define STAGE(P, BASE, OFF, kt) do { \
;     __builtin_amdgcn_global_load_lds((const unsigned*)((BASE) + (OFF[0] + (unsigned)(kt) * BK)), (unsigned*)((char*)(P) + wid * 1024), 16, 0, 0); \
;     __builtin_amdgcn_global_load_lds((const unsigned*)((BASE) + (OFF[1] + (unsigned)(kt) * BK)), (unsigned*)((char*)(P) + wid * 1024 + 8192), 16, 0, 0); } while (0)
; #define LDA(dst, b, h) for (int m = 0; m < 4; ++m) for (int k = 0; k < 2; ++k) \
;     dst[m][k] = *reinterpret_cast<const bf16x8*>((char*)SA(b, h) + lds_byte(wr * 64 + m * 16 + fr, k * 32 + fq * 8))
; #define LDB(dst, b, h) for (int n = 0; n < 2; ++n) for (int k = 0; k < 2; ++k) \
;     dst[n][k] = *reinterpret_cast<const bf16x8*>((char*)SB(b, h) + lds_byte(wc * 32 + n * 16 + fr, k * 32 + fq * 8))
; #define MMA(ai, bj, At_, Bt_) do { __builtin_amdgcn_s_setprio(1); \
;     for (int m = 0; m < 4; ++m) for (int n = 0; n < 2; ++n) for (int k = 0; k < 2; ++k) \
;       acc[ai][bj][m][n] = __builtin_amdgcn_mfma_f32_16x16x32_bf16(Bt_[n][k], At_[m][k], acc[ai][bj][m][n], 0, 0, 0); \
;     __builtin_amdgcn_s_setprio(0); } while (0)
; #define BAR __builtin_amdgcn_s_barrier()
; #define SCHED __builtin_amdgcn_sched_barrier(0)
; DEVI void gemm_tile(const Params& p, int layer, const u16* __restrict__ A, unsigned lda, const u16* __restrict__ Bt, unsigned ldb, int K,
;                     int brow, int bcol, int ekind, const int tid_) {
;     ...
;     LDB(B0, 0, 0); SCHED; LDA(At, 0, 0); STAGE(SA(1, 1), A1, offA, t + 1);
;     WAIT_L(8); BAR; WAIT_L(0); MMA(0, 0, At, B0); BAR; SCHED;
;     LDB(B1, 0, 1); STAGE(SB(0, 0), B0p, offB, t + 2);
;     BAR; WAIT_L(0); MMA(0, 1, At, B1); BAR;
;     LDA(At, 0, 1); STAGE(SA(0, 0), A0, offA, t + 2);
;     BAR; WAIT_L(0); MMA(1, 0, At, B0); BAR; SCHED;
.LBB0_313:
	ds_read_b128 v[180:183], v161
	ds_read_b128 v[184:187], v161 offset:1024
	ds_read_b128 v[188:191], v161 offset:2048
	ds_read_b128 v[192:195], v161 offset:3072
	v_add_u32_e32 v168, s11, v162
	v_add_u32_e32 v164, 0xc000, v145
	v_add_u32_e32 v0, 64, v168
	v_readfirstlane_b32 s45, v164
	v_add_u32_e32 v179, s11, v160
	v_add_u32_e32 v165, 0xe000, v145
	v_lshl_add_u64 v[166:167], v[0:1], 1, s[2:3]
	s_mov_b32 m0, s45
	v_add_u32_e32 v0, 64, v179
	v_readfirstlane_b32 s45, v165
	ds_read_b128 v[196:199], v141
	ds_read_b128 v[200:203], v141 offset:1024
	ds_read_b128 v[204:207], v140
	ds_read_b128 v[208:211], v140 offset:1024
	ds_read_b128 v[212:215], v139
	ds_read_b128 v[216:219], v139 offset:1024
	ds_read_b128 v[220:223], v138
	ds_read_b128 v[224:227], v138 offset:1024
	global_load_lds_dwordx4 v[166:167], off
	s_mov_b32 m0, s45
	v_lshl_add_u64 v[166:167], v[0:1], 1, s[2:3]
	global_load_lds_dwordx4 v[166:167], off
	s_waitcnt lgkmcnt(8)
	s_barrier
	s_waitcnt lgkmcnt(0)
	s_setprio 1
	v_mfma_f32_16x16x32_bf16 v[126:129], v[180:183], v[196:199], v[126:129]
	v_mfma_f32_16x16x32_bf16 v[122:125], v[188:191], v[196:199], v[122:125]
	v_mfma_f32_16x16x32_bf16 v[118:121], v[180:183], v[204:207], v[118:121]
	v_mfma_f32_16x16x32_bf16 v[114:117], v[188:191], v[204:207], v[114:117]
	v_mfma_f32_16x16x32_bf16 v[110:113], v[180:183], v[212:215], v[110:113]
	v_mfma_f32_16x16x32_bf16 v[106:109], v[188:191], v[212:215], v[106:109]
	v_mfma_f32_16x16x32_bf16 v[102:105], v[180:183], v[220:223], v[102:105]
	v_mfma_f32_16x16x32_bf16 v[98:101], v[188:191], v[220:223], v[98:101]
	v_mfma_f32_16x16x32_bf16 v[126:129], v[184:187], v[200:203], v[126:129]
	v_mfma_f32_16x16x32_bf16 v[122:125], v[192:195], v[200:203], v[122:125]
	v_mfma_f32_16x16x32_bf16 v[118:121], v[184:187], v[208:211], v[118:121]
	v_mfma_f32_16x16x32_bf16 v[114:117], v[192:195], v[208:211], v[114:117]
	v_mfma_f32_16x16x32_bf16 v[110:113], v[184:187], v[216:219], v[110:113]
	v_mfma_f32_16x16x32_bf16 v[106:109], v[192:195], v[216:219], v[106:109]
	v_mfma_f32_16x16x32_bf16 v[102:105], v[184:187], v[224:227], v[102:105]
	v_mfma_f32_16x16x32_bf16 v[98:101], v[192:195], v[224:227], v[98:101]
	s_setprio 0
	s_barrier
	v_add_u32_e32 v252, s11, v163
	v_add_u32_e32 v0, 0x80, v252
	v_lshlrev_b64 v[166:167], 1, v[0:1]
	v_readfirstlane_b32 s45, v143
	v_add_u32_e32 v169, s11, v134
	v_lshl_add_u64 v[244:245], s[6:7], 0, v[166:167]
	s_mov_b32 m0, s45
	v_add_u32_e32 v0, 0x80, v169
	ds_read_b128 v[228:231], v156
	ds_read_b128 v[232:235], v156 offset:1024
	ds_read_b128 v[236:239], v156 offset:2048
	ds_read_b128 v[240:243], v156 offset:3072
	global_load_lds_dwordx4 v[244:245], off
	v_lshlrev_b64 v[244:245], 1, v[0:1]
	v_readfirstlane_b32 s45, v144
	v_lshl_add_u64 v[246:247], s[6:7], 0, v[244:245]
	s_mov_b32 m0, s45
	s_add_i32 s42, s42, 2
	global_load_lds_dwordx4 v[246:247], off
	s_barrier
	s_waitcnt lgkmcnt(0)
	s_setprio 1
	v_mfma_f32_16x16x32_bf16 v[94:97], v[228:231], v[196:199], v[94:97]
	v_mfma_f32_16x16x32_bf16 v[90:93], v[236:239], v[196:199], v[90:93]
	v_mfma_f32_16x16x32_bf16 v[86:89], v[228:231], v[204:207], v[86:89]
	v_mfma_f32_16x16x32_bf16 v[82:85], v[236:239], v[204:207], v[82:85]
	v_mfma_f32_16x16x32_bf16 v[78:81], v[228:231], v[212:215], v[78:81]
	v_mfma_f32_16x16x32_bf16 v[74:77], v[236:239], v[212:215], v[74:77]
	v_mfma_f32_16x16x32_bf16 v[70:73], v[228:231], v[220:223], v[70:73]
	v_mfma_f32_16x16x32_bf16 v[66:69], v[236:239], v[220:223], v[66:69]
	v_mfma_f32_16x16x32_bf16 v[94:97], v[232:235], v[200:203], v[94:97]
	v_mfma_f32_16x16x32_bf16 v[90:93], v[240:243], v[200:203], v[90:93]
	v_mfma_f32_16x16x32_bf16 v[86:89], v[232:235], v[208:211], v[86:89]
	v_mfma_f32_16x16x32_bf16 v[82:85], v[240:243], v[208:211], v[82:85]
	v_mfma_f32_16x16x32_bf16 v[78:81], v[232:235], v[216:219], v[78:81]
	v_mfma_f32_16x16x32_bf16 v[74:77], v[240:243], v[216:219], v[74:77]
	v_mfma_f32_16x16x32_bf16 v[70:73], v[232:235], v[224:227], v[70:73]
	v_mfma_f32_16x16x32_bf16 v[66:69], v[240:243], v[224:227], v[66:69]
	s_setprio 0
	v_add_u32_e32 v0, 0x80, v168
	v_lshlrev_b64 v[246:247], 1, v[0:1]
	v_readfirstlane_b32 s45, v145
	v_lshl_add_u64 v[248:249], s[4:5], 0, v[246:247]
	s_mov_b32 m0, s45
	v_add_u32_e32 v0, 0x80, v179
	s_barrier
	ds_read_b128 v[196:199], v141 offset:16384
	ds_read_b128 v[200:203], v141 offset:17408
	ds_read_b128 v[204:207], v140 offset:16384
	ds_read_b128 v[208:211], v140 offset:17408
	ds_read_b128 v[212:215], v139 offset:16384
	ds_read_b128 v[216:219], v139 offset:17408
	ds_read_b128 v[220:223], v138 offset:16384
	ds_read_b128 v[224:227], v138 offset:17408
	global_load_lds_dwordx4 v[248:249], off
	v_lshlrev_b64 v[248:249], 1, v[0:1]
	v_readfirstlane_b32 s45, v148
	s_mov_b32 m0, s45
	v_lshl_add_u64 v[250:251], s[4:5], 0, v[248:249]
	global_load_lds_dwordx4 v[250:251], off
	s_barrier
	s_waitcnt lgkmcnt(0)
	s_setprio 1
	v_mfma_f32_16x16x32_bf16 v[62:65], v[180:183], v[196:199], v[62:65]
	v_mfma_f32_16x16x32_bf16 v[58:61], v[188:191], v[196:199], v[58:61]
	v_mfma_f32_16x16x32_bf16 v[54:57], v[180:183], v[204:207], v[54:57]
	v_mfma_f32_16x16x32_bf16 v[50:53], v[188:191], v[204:207], v[50:53]
	v_mfma_f32_16x16x32_bf16 v[46:49], v[180:183], v[212:215], v[46:49]
	v_mfma_f32_16x16x32_bf16 v[42:45], v[188:191], v[212:215], v[42:45]
	v_mfma_f32_16x16x32_bf16 v[38:41], v[180:183], v[220:223], v[38:41]
	v_mfma_f32_16x16x32_bf16 v[34:37], v[188:191], v[220:223], v[34:37]
	v_mfma_f32_16x16x32_bf16 v[62:65], v[184:187], v[200:203], v[62:65]
	v_mfma_f32_16x16x32_bf16 v[58:61], v[192:195], v[200:203], v[58:61]
	v_mfma_f32_16x16x32_bf16 v[54:57], v[184:187], v[208:211], v[54:57]
	v_mfma_f32_16x16x32_bf16 v[50:53], v[192:195], v[208:211], v[50:53]
	v_mfma_f32_16x16x32_bf16 v[46:49], v[184:187], v[216:219], v[46:49]
	v_mfma_f32_16x16x32_bf16 v[42:45], v[192:195], v[216:219], v[42:45]
	v_mfma_f32_16x16x32_bf16 v[38:41], v[184:187], v[224:227], v[38:41]
	v_mfma_f32_16x16x32_bf16 v[34:37], v[192:195], v[224:227], v[34:37]
	s_setprio 0
	s_barrier
; #define WAIT_V(n) asm volatile("s_waitcnt vmcnt(%0)" ::"n"(n) : "memory")
; #define WAIT_L(n) asm volatile("s_waitcnt lgkmcnt(%0)" ::"n"(n) : "memory")
; #define STAGE(P, BASE, OFF, kt) do { \
;     __builtin_amdgcn_global_load_lds((const unsigned*)((BASE) + (OFF[0] + (unsigned)(kt) * BK)), (unsigned*)((char*)(P) + wid * 1024), 16, 0, 0); \
;     __builtin_amdgcn_global_load_lds((const unsigned*)((BASE) + (OFF[1] + (unsigned)(kt) * BK)), (unsigned*)((char*)(P) + wid * 1024 + 8192), 16, 0, 0); } while (0)
; #define LDA(dst, b, h) for (int m = 0; m < 4; ++m) for (int k = 0; k < 2; ++k) \
;     dst[m][k] = *reinterpret_cast<const bf16x8*>((char*)SA(b, h) + lds_byte(wr * 64 + m * 16 + fr, k * 32 + fq * 8))
; #define LDB(dst, b, h) for (int n = 0; n < 2; ++n) for (int k = 0; k < 2; ++k) \
;     dst[n][k] = *reinterpret_cast<const bf16x8*>((char*)SB(b, h) + lds_byte(wc * 32 + n * 16 + fr, k * 32 + fq * 8))
; #define MMA(ai, bj, At_, Bt_) do { __builtin_amdgcn_s_setprio(1); \
;     for (int m = 0; m < 4; ++m) for (int n = 0; n < 2; ++n) for (int k = 0; k < 2; ++k) \
;       acc[ai][bj][m][n] = __builtin_amdgcn_mfma_f32_16x16x32_bf16(Bt_[n][k], At_[m][k], acc[ai][bj][m][n], 0, 0, 0); \
;     __builtin_amdgcn_s_setprio(0); } while (0)
; #define BAR __builtin_amdgcn_s_barrier()
; #define SCHED __builtin_amdgcn_sched_barrier(0)
; DEVI void gemm_tile(const Params& p, int layer, const u16* __restrict__ A, unsigned lda, const u16* __restrict__ Bt, unsigned ldb, int K,
;                     int brow, int bcol, int ekind, const int tid_) {
;     ...
;     STAGE(SB(0, 1), B1p, offB, t + 2);
;     WAIT_V(6); BAR; MMA(1, 1, At, B1); BAR;
;     LDB(B0, 1, 0); SCHED; LDA(At, 1, 0); STAGE(SA(0, 1), A1, offA, t + 2);
;     WAIT_L(8); BAR; WAIT_L(0); MMA(0, 0, At, B0); BAR; SCHED;
;     LDB(B1, 1, 1); STAGE(SB(1, 0), B0p, offB, t + 3);
;     BAR; WAIT_L(0); MMA(0, 1, At, B1); BAR;
;     LDA(At, 1, 1); STAGE(SA(1, 0), A0, offA, t + 3);
	v_readfirstlane_b32 s45, v149
	v_lshl_add_u64 v[166:167], s[8:9], 0, v[166:167]
	s_mov_b32 m0, s45
	v_readfirstlane_b32 s45, v150
	global_load_lds_dwordx4 v[166:167], off
	s_mov_b32 m0, s45
	v_lshl_add_u64 v[166:167], s[8:9], 0, v[244:245]
	global_load_lds_dwordx4 v[166:167], off
	s_waitcnt vmcnt(6)
	s_barrier
	s_setprio 1
	v_mfma_f32_16x16x32_bf16 v[30:33], v[228:231], v[196:199], v[30:33]
	v_mfma_f32_16x16x32_bf16 v[26:29], v[236:239], v[196:199], v[26:29]
	v_mfma_f32_16x16x32_bf16 v[22:25], v[228:231], v[204:207], v[22:25]
	v_mfma_f32_16x16x32_bf16 v[18:21], v[236:239], v[204:207], v[18:21]
	v_mfma_f32_16x16x32_bf16 v[14:17], v[228:231], v[212:215], v[14:17]
	v_mfma_f32_16x16x32_bf16 v[10:13], v[236:239], v[212:215], v[10:13]
	v_mfma_f32_16x16x32_bf16 v[6:9], v[228:231], v[220:223], v[6:9]
	v_mfma_f32_16x16x32_bf16 v[2:5], v[236:239], v[220:223], v[2:5]
	v_mfma_f32_16x16x32_bf16 v[30:33], v[232:235], v[200:203], v[30:33]
	v_mfma_f32_16x16x32_bf16 v[26:29], v[240:243], v[200:203], v[26:29]
	v_mfma_f32_16x16x32_bf16 v[22:25], v[232:235], v[208:211], v[22:25]
	v_mfma_f32_16x16x32_bf16 v[18:21], v[240:243], v[208:211], v[18:21]
	v_mfma_f32_16x16x32_bf16 v[14:17], v[232:235], v[216:219], v[14:17]
	v_mfma_f32_16x16x32_bf16 v[10:13], v[240:243], v[216:219], v[10:13]
	v_mfma_f32_16x16x32_bf16 v[6:9], v[232:235], v[224:227], v[6:9]
	v_mfma_f32_16x16x32_bf16 v[2:5], v[240:243], v[224:227], v[2:5]
	s_setprio 0
	s_barrier
	ds_read_b128 v[180:183], v147
	ds_read_b128 v[184:187], v147 offset:1024
	ds_read_b128 v[188:191], v147 offset:2048
	ds_read_b128 v[192:195], v147 offset:3072
	v_readfirstlane_b32 s45, v151
	v_lshl_add_u64 v[166:167], s[2:3], 0, v[246:247]
	s_mov_b32 m0, s45
	v_readfirstlane_b32 s45, v152
	ds_read_b128 v[196:199], v141 offset:32768
	ds_read_b128 v[200:203], v141 offset:33792
	ds_read_b128 v[204:207], v140 offset:32768
	ds_read_b128 v[208:211], v140 offset:33792
	ds_read_b128 v[212:215], v139 offset:32768
	ds_read_b128 v[216:219], v139 offset:33792
	ds_read_b128 v[220:223], v138 offset:32768
	ds_read_b128 v[224:227], v138 offset:33792
	global_load_lds_dwordx4 v[166:167], off
	s_mov_b32 m0, s45
	v_lshl_add_u64 v[166:167], s[2:3], 0, v[248:249]
	global_load_lds_dwordx4 v[166:167], off
	s_waitcnt lgkmcnt(8)
	s_barrier
	s_waitcnt lgkmcnt(0)
	s_setprio 1
	v_mfma_f32_16x16x32_bf16 v[126:129], v[180:183], v[196:199], v[126:129]
	v_mfma_f32_16x16x32_bf16 v[122:125], v[188:191], v[196:199], v[122:125]
	v_mfma_f32_16x16x32_bf16 v[118:121], v[180:183], v[204:207], v[118:121]
	v_mfma_f32_16x16x32_bf16 v[114:117], v[188:191], v[204:207], v[114:117]
	v_mfma_f32_16x16x32_bf16 v[110:113], v[180:183], v[212:215], v[110:113]
	v_mfma_f32_16x16x32_bf16 v[106:109], v[188:191], v[212:215], v[106:109]
	v_mfma_f32_16x16x32_bf16 v[102:105], v[180:183], v[220:223], v[102:105]
	v_mfma_f32_16x16x32_bf16 v[98:101], v[188:191], v[220:223], v[98:101]
	v_mfma_f32_16x16x32_bf16 v[126:129], v[184:187], v[200:203], v[126:129]
	v_mfma_f32_16x16x32_bf16 v[122:125], v[192:195], v[200:203], v[122:125]
	v_mfma_f32_16x16x32_bf16 v[118:121], v[184:187], v[208:211], v[118:121]
	v_mfma_f32_16x16x32_bf16 v[114:117], v[192:195], v[208:211], v[114:117]
	v_mfma_f32_16x16x32_bf16 v[110:113], v[184:187], v[216:219], v[110:113]
	v_mfma_f32_16x16x32_bf16 v[106:109], v[192:195], v[216:219], v[106:109]
	v_mfma_f32_16x16x32_bf16 v[102:105], v[184:187], v[224:227], v[102:105]
	v_mfma_f32_16x16x32_bf16 v[98:101], v[192:195], v[224:227], v[98:101]
	s_setprio 0
	s_barrier
	v_add_u32_e32 v0, 0xc0, v252
	v_lshlrev_b64 v[166:167], 1, v[0:1]
	v_readfirstlane_b32 s45, v153
	v_lshl_add_u64 v[244:245], s[6:7], 0, v[166:167]
	s_mov_b32 m0, s45
	v_add_u32_e32 v0, 0xc0, v169
	ds_read_b128 v[228:231], v142
	ds_read_b128 v[232:235], v142 offset:1024
	ds_read_b128 v[236:239], v142 offset:2048
	ds_read_b128 v[240:243], v142 offset:3072
	global_load_lds_dwordx4 v[244:245], off
	v_lshlrev_b64 v[244:245], 1, v[0:1]
	v_readfirstlane_b32 s45, v154
	s_mov_b32 m0, s45
	v_lshl_add_u64 v[246:247], s[6:7], 0, v[244:245]
	global_load_lds_dwordx4 v[246:247], off
	s_barrier
	s_waitcnt lgkmcnt(0)
	s_setprio 1
	v_mfma_f32_16x16x32_bf16 v[94:97], v[228:231], v[196:199], v[94:97]
	v_mfma_f32_16x16x32_bf16 v[90:93], v[236:239], v[196:199], v[90:93]
	v_mfma_f32_16x16x32_bf16 v[86:89], v[228:231], v[204:207], v[86:89]
	v_mfma_f32_16x16x32_bf16 v[82:85], v[236:239], v[204:207], v[82:85]
	v_mfma_f32_16x16x32_bf16 v[78:81], v[228:231], v[212:215], v[78:81]
	v_mfma_f32_16x16x32_bf16 v[74:77], v[236:239], v[212:215], v[74:77]
	v_mfma_f32_16x16x32_bf16 v[70:73], v[228:231], v[220:223], v[70:73]
	v_mfma_f32_16x16x32_bf16 v[66:69], v[236:239], v[220:223], v[66:69]
	v_mfma_f32_16x16x32_bf16 v[94:97], v[232:235], v[200:203], v[94:97]
	v_mfma_f32_16x16x32_bf16 v[90:93], v[240:243], v[200:203], v[90:93]
	v_mfma_f32_16x16x32_bf16 v[86:89], v[232:235], v[208:211], v[86:89]
	v_mfma_f32_16x16x32_bf16 v[82:85], v[240:243], v[208:211], v[82:85]
	v_mfma_f32_16x16x32_bf16 v[78:81], v[232:235], v[216:219], v[78:81]
	v_mfma_f32_16x16x32_bf16 v[74:77], v[240:243], v[216:219], v[74:77]
	v_mfma_f32_16x16x32_bf16 v[70:73], v[232:235], v[224:227], v[70:73]
	v_mfma_f32_16x16x32_bf16 v[66:69], v[240:243], v[224:227], v[66:69]
	s_setprio 0
	v_add_u32_e32 v0, 0xc0, v168
	v_readfirstlane_b32 s45, v155
	v_lshl_add_u64 v[246:247], v[0:1], 1, s[4:5]
	s_mov_b32 m0, s45
	v_add_u32_e32 v0, 0xc0, v179
	v_readfirstlane_b32 s45, v157
	s_barrier
; #define WAIT_V(n) asm volatile("s_waitcnt vmcnt(%0)" ::"n"(n) : "memory")
; #define WAIT_L(n) asm volatile("s_waitcnt lgkmcnt(%0)" ::"n"(n) : "memory")
; #define STAGE(P, BASE, OFF, kt) do { \
;     __builtin_amdgcn_global_load_lds((const unsigned*)((BASE) + (OFF[0] + (unsigned)(kt) * BK)), (unsigned*)((char*)(P) + wid * 1024), 16, 0, 0); \
;     __builtin_amdgcn_global_load_lds((const unsigned*)((BASE) + (OFF[1] + (unsigned)(kt) * BK)), (unsigned*)((char*)(P) + wid * 1024 + 8192), 16, 0, 0); } while (0)
; #define LDA(dst, b, h) for (int m = 0; m < 4; ++m) for (int k = 0; k < 2; ++k) \
;     dst[m][k] = *reinterpret_cast<const bf16x8*>((char*)SA(b, h) + lds_byte(wr * 64 + m * 16 + fr, k * 32 + fq * 8))
; #define LDB(dst, b, h) for (int n = 0; n < 2; ++n) for (int k = 0; k < 2; ++k) \
;     dst[n][k] = *reinterpret_cast<const bf16x8*>((char*)SB(b, h) + lds_byte(wc * 32 + n * 16 + fr, k * 32 + fq * 8))
; #define MMA(ai, bj, At_, Bt_) do { __builtin_amdgcn_s_setprio(1); \
;     for (int m = 0; m < 4; ++m) for (int n = 0; n < 2; ++n) for (int k = 0; k < 2; ++k) \
;       acc[ai][bj][m][n] = __builtin_amdgcn_mfma_f32_16x16x32_bf16(Bt_[n][k], At_[m][k], acc[ai][bj][m][n], 0, 0, 0); \
;     __builtin_amdgcn_s_setprio(0); } while (0)
; #define BAR __builtin_amdgcn_s_barrier()
; #define SCHED __builtin_amdgcn_sched_barrier(0)
; DEVI void gemm_tile(const Params& p, int layer, const u16* __restrict__ A, unsigned lda, const u16* __restrict__ Bt, unsigned ldb, int K,
;                     int brow, int bcol, int ekind, const int tid_) {
;     ...
;     LDA(At, 1, 1); STAGE(SA(1, 0), A0, offA, t + 3);
;     BAR; WAIT_L(0); MMA(1, 0, At, B0); BAR; SCHED;
;     STAGE(SB(1, 1), B1p, offB, t + 3);
;     WAIT_V(6); BAR; MMA(1, 1, At, B1); BAR;
;   }
;   { LDB(B0, 0, 0); LDA(At, 0, 0); STAGE(SA(1, 1), A1, offA, nt - 1);
;     BAR; WAIT_L(0); MMA(0, 0, At, B0); BAR;
;     LDB(B1, 0, 1); BAR; WAIT_L(0); MMA(0, 1, At, B1); BAR;
	ds_read_b128 v[196:199], v141 offset:49152
	ds_read_b128 v[200:203], v141 offset:50176
	ds_read_b128 v[204:207], v140 offset:49152
	ds_read_b128 v[208:211], v140 offset:50176
	ds_read_b128 v[212:215], v139 offset:49152
	ds_read_b128 v[216:219], v139 offset:50176
	ds_read_b128 v[220:223], v138 offset:49152
	ds_read_b128 v[224:227], v138 offset:50176
	global_load_lds_dwordx4 v[246:247], off
	s_mov_b32 m0, s45
	v_lshl_add_u64 v[246:247], v[0:1], 1, s[4:5]
	global_load_lds_dwordx4 v[246:247], off
	s_barrier
	s_waitcnt lgkmcnt(0)
	s_setprio 1
	v_mfma_f32_16x16x32_bf16 v[62:65], v[180:183], v[196:199], v[62:65]
	v_mfma_f32_16x16x32_bf16 v[58:61], v[188:191], v[196:199], v[58:61]
	v_mfma_f32_16x16x32_bf16 v[54:57], v[180:183], v[204:207], v[54:57]
	v_mfma_f32_16x16x32_bf16 v[50:53], v[188:191], v[204:207], v[50:53]
	v_mfma_f32_16x16x32_bf16 v[46:49], v[180:183], v[212:215], v[46:49]
	v_mfma_f32_16x16x32_bf16 v[42:45], v[188:191], v[212:215], v[42:45]
	v_mfma_f32_16x16x32_bf16 v[38:41], v[180:183], v[220:223], v[38:41]
	v_mfma_f32_16x16x32_bf16 v[34:37], v[188:191], v[220:223], v[34:37]
	v_mfma_f32_16x16x32_bf16 v[62:65], v[184:187], v[200:203], v[62:65]
	v_mfma_f32_16x16x32_bf16 v[58:61], v[192:195], v[200:203], v[58:61]
	v_mfma_f32_16x16x32_bf16 v[54:57], v[184:187], v[208:211], v[54:57]
	v_mfma_f32_16x16x32_bf16 v[50:53], v[192:195], v[208:211], v[50:53]
	v_mfma_f32_16x16x32_bf16 v[46:49], v[184:187], v[216:219], v[46:49]
	v_mfma_f32_16x16x32_bf16 v[42:45], v[192:195], v[216:219], v[42:45]
	v_mfma_f32_16x16x32_bf16 v[38:41], v[184:187], v[224:227], v[38:41]
	v_mfma_f32_16x16x32_bf16 v[34:37], v[192:195], v[224:227], v[34:37]
	s_setprio 0
	s_barrier
	v_readfirstlane_b32 s45, v158
	v_lshl_add_u64 v[166:167], s[8:9], 0, v[166:167]
	s_mov_b32 m0, s45
	v_readfirstlane_b32 s45, v159
	global_load_lds_dwordx4 v[166:167], off
	s_mov_b32 m0, s45
	v_lshl_add_u64 v[166:167], s[8:9], 0, v[244:245]
	global_load_lds_dwordx4 v[166:167], off
	s_waitcnt vmcnt(6)
	s_barrier
	s_setprio 1
	v_mfma_f32_16x16x32_bf16 v[30:33], v[228:231], v[196:199], v[30:33]
	v_mfma_f32_16x16x32_bf16 v[26:29], v[236:239], v[196:199], v[26:29]
	v_mfma_f32_16x16x32_bf16 v[22:25], v[228:231], v[204:207], v[22:25]
	v_mfma_f32_16x16x32_bf16 v[18:21], v[236:239], v[204:207], v[18:21]
	v_mfma_f32_16x16x32_bf16 v[14:17], v[228:231], v[212:215], v[14:17]
	v_mfma_f32_16x16x32_bf16 v[10:13], v[236:239], v[212:215], v[10:13]
	v_mfma_f32_16x16x32_bf16 v[6:9], v[228:231], v[220:223], v[6:9]
	v_mfma_f32_16x16x32_bf16 v[2:5], v[236:239], v[220:223], v[2:5]
	v_mfma_f32_16x16x32_bf16 v[30:33], v[232:235], v[200:203], v[30:33]
	v_mfma_f32_16x16x32_bf16 v[26:29], v[240:243], v[200:203], v[26:29]
	v_mfma_f32_16x16x32_bf16 v[22:25], v[232:235], v[208:211], v[22:25]
	v_mfma_f32_16x16x32_bf16 v[18:21], v[240:243], v[208:211], v[18:21]
	v_mfma_f32_16x16x32_bf16 v[14:17], v[232:235], v[216:219], v[14:17]
	v_mfma_f32_16x16x32_bf16 v[10:13], v[240:243], v[216:219], v[10:13]
	v_mfma_f32_16x16x32_bf16 v[6:9], v[232:235], v[224:227], v[6:9]
	v_mfma_f32_16x16x32_bf16 v[2:5], v[240:243], v[224:227], v[2:5]
	s_setprio 0
	s_addk_i32 s11, 0x80
	s_cmp_lt_u32 s42, s10
	s_barrier
	s_cbranch_scc1 .LBB0_313
	s_sub_i32 s4, s66, 64
	v_add_u32_e32 v0, s4, v130
	v_readfirstlane_b32 s5, v164
	v_lshl_add_u64 v[144:145], v[0:1], 1, s[2:3]
	s_mov_b32 m0, s5
	v_add_u32_e32 v0, s4, v132
	ds_read_b128 v[148:151], v161
	ds_read_b128 v[152:155], v161 offset:1024
	ds_read_b128 v[180:183], v161 offset:2048
	ds_read_b128 v[158:161], v161 offset:3072
	ds_read_b128 v[184:187], v141
	ds_read_b128 v[188:191], v141 offset:1024
	ds_read_b128 v[192:195], v140
	ds_read_b128 v[196:199], v140 offset:1024
	ds_read_b128 v[200:203], v139
	ds_read_b128 v[204:207], v139 offset:1024
	ds_read_b128 v[208:211], v138
	ds_read_b128 v[212:215], v138 offset:1024
	global_load_lds_dwordx4 v[144:145], off
	v_lshl_add_u64 v[144:145], v[0:1], 1, s[2:3]
	v_readfirstlane_b32 s2, v165
	s_mov_b32 m0, s2
	s_nop 0
	global_load_lds_dwordx4 v[144:145], off
	s_barrier
	s_waitcnt lgkmcnt(0)
	s_setprio 1
	v_mfma_f32_16x16x32_bf16 v[126:129], v[148:151], v[184:187], v[126:129]
	v_mfma_f32_16x16x32_bf16 v[122:125], v[180:183], v[184:187], v[122:125]
	v_mfma_f32_16x16x32_bf16 v[118:121], v[148:151], v[192:195], v[118:121]
	v_mfma_f32_16x16x32_bf16 v[114:117], v[180:183], v[192:195], v[114:117]
	v_mfma_f32_16x16x32_bf16 v[102:105], v[148:151], v[208:211], v[102:105]
	v_mfma_f32_16x16x32_bf16 v[98:101], v[180:183], v[208:211], v[98:101]
	v_mfma_f32_16x16x32_bf16 v[126:129], v[152:155], v[188:191], v[126:129]
	v_mfma_f32_16x16x32_bf16 v[122:125], v[158:161], v[188:191], v[122:125]
	v_mfma_f32_16x16x32_bf16 v[118:121], v[152:155], v[196:199], v[118:121]
	v_mfma_f32_16x16x32_bf16 v[114:117], v[158:161], v[196:199], v[114:117]
	v_mfma_f32_16x16x32_bf16 v[110:113], v[148:151], v[200:203], v[110:113]
	v_mfma_f32_16x16x32_bf16 v[106:109], v[180:183], v[200:203], v[106:109]
	v_mfma_f32_16x16x32_bf16 v[102:105], v[152:155], v[212:215], v[102:105]
	v_mfma_f32_16x16x32_bf16 v[98:101], v[158:161], v[212:215], v[98:101]
	v_mfma_f32_16x16x32_bf16 v[162:165], v[152:155], v[204:207], v[110:113]
	v_mfma_f32_16x16x32_bf16 v[216:219], v[158:161], v[204:207], v[106:109]
	s_setprio 0
	s_barrier
	s_nop 1
	ds_read_b128 v[106:109], v156
	ds_read_b128 v[110:113], v156 offset:1024
	ds_read_b128 v[220:223], v156 offset:2048
	ds_read_b128 v[224:227], v156 offset:3072
	s_barrier
; #define WAIT_V(n) asm volatile("s_waitcnt vmcnt(%0)" ::"n"(n) : "memory")
; #define WAIT_L(n) asm volatile("s_waitcnt lgkmcnt(%0)" ::"n"(n) : "memory")
; #define LDA(dst, b, h) for (int m = 0; m < 4; ++m) for (int k = 0; k < 2; ++k) \
;     dst[m][k] = *reinterpret_cast<const bf16x8*>((char*)SA(b, h) + lds_byte(wr * 64 + m * 16 + fr, k * 32 + fq * 8))
; #define LDB(dst, b, h) for (int n = 0; n < 2; ++n) for (int k = 0; k < 2; ++k) \
;     dst[n][k] = *reinterpret_cast<const bf16x8*>((char*)SB(b, h) + lds_byte(wc * 32 + n * 16 + fr, k * 32 + fq * 8))
; #define MMA(ai, bj, At_, Bt_) do { __builtin_amdgcn_s_setprio(1); \
;     for (int m = 0; m < 4; ++m) for (int n = 0; n < 2; ++n) for (int k = 0; k < 2; ++k) \
;       acc[ai][bj][m][n] = __builtin_amdgcn_mfma_f32_16x16x32_bf16(Bt_[n][k], At_[m][k], acc[ai][bj][m][n], 0, 0, 0); \
;     __builtin_amdgcn_s_setprio(0); } while (0)
; #define BAR __builtin_amdgcn_s_barrier()
; DEVI void gemm_tile(const Params& p, int layer, const u16* __restrict__ A, unsigned lda, const u16* __restrict__ Bt, unsigned ldb, int K,
;                     int brow, int bcol, int ekind, const int tid_) {
;     ...
;     LDB(B1, 0, 1); BAR; WAIT_L(0); MMA(0, 1, At, B1); BAR;
;     LDA(At, 0, 1); WAIT_V(4); BAR; WAIT_L(0); MMA(1, 0, At, B0); MMA(1, 1, At, B1); BAR; }
;   { LDB(B0, 1, 0); LDA(At, 1, 0); WAIT_V(2); BAR; WAIT_L(0); MMA(0, 0, At, B0); BAR;
	s_waitcnt lgkmcnt(0)
	s_setprio 1
	v_mfma_f32_16x16x32_bf16 v[86:89], v[106:109], v[192:195], v[86:89]
	v_mfma_f32_16x16x32_bf16 v[82:85], v[220:223], v[192:195], v[82:85]
	v_mfma_f32_16x16x32_bf16 v[70:73], v[106:109], v[208:211], v[70:73]
	v_mfma_f32_16x16x32_bf16 v[66:69], v[220:223], v[208:211], v[66:69]
	v_mfma_f32_16x16x32_bf16 v[94:97], v[106:109], v[184:187], v[94:97]
	v_mfma_f32_16x16x32_bf16 v[90:93], v[220:223], v[184:187], v[90:93]
	v_mfma_f32_16x16x32_bf16 v[86:89], v[110:113], v[196:199], v[86:89]
	v_mfma_f32_16x16x32_bf16 v[82:85], v[224:227], v[196:199], v[82:85]
	v_mfma_f32_16x16x32_bf16 v[78:81], v[106:109], v[200:203], v[78:81]
	v_mfma_f32_16x16x32_bf16 v[74:77], v[220:223], v[200:203], v[74:77]
	v_mfma_f32_16x16x32_bf16 v[70:73], v[110:113], v[212:215], v[70:73]
	v_mfma_f32_16x16x32_bf16 v[66:69], v[224:227], v[212:215], v[66:69]
	v_mfma_f32_16x16x32_bf16 v[228:231], v[110:113], v[188:191], v[94:97]
	v_mfma_f32_16x16x32_bf16 v[184:187], v[224:227], v[188:191], v[90:93]
	v_mfma_f32_16x16x32_bf16 v[188:191], v[110:113], v[204:207], v[78:81]
	v_mfma_f32_16x16x32_bf16 v[192:195], v[224:227], v[204:207], v[74:77]
	s_setprio 0
	s_barrier
	s_nop 0
	ds_read_b128 v[74:77], v141 offset:16384
	ds_read_b128 v[78:81], v141 offset:17408
	ds_read_b128 v[90:93], v140 offset:16384
	ds_read_b128 v[94:97], v140 offset:17408
	ds_read_b128 v[196:199], v139 offset:16384
	ds_read_b128 v[200:203], v139 offset:17408
	ds_read_b128 v[204:207], v138 offset:16384
	ds_read_b128 v[208:211], v138 offset:17408
	s_waitcnt vmcnt(4)
	s_barrier
	s_waitcnt lgkmcnt(0)
	s_setprio 1
	v_mfma_f32_16x16x32_bf16 v[62:65], v[148:151], v[74:77], v[62:65]
	v_mfma_f32_16x16x32_bf16 v[58:61], v[180:183], v[74:77], v[58:61]
	v_mfma_f32_16x16x32_bf16 v[54:57], v[148:151], v[90:93], v[54:57]
	v_mfma_f32_16x16x32_bf16 v[50:53], v[180:183], v[90:93], v[50:53]
	v_mfma_f32_16x16x32_bf16 v[38:41], v[148:151], v[204:207], v[38:41]
	v_mfma_f32_16x16x32_bf16 v[34:37], v[180:183], v[204:207], v[34:37]
	v_mfma_f32_16x16x32_bf16 v[62:65], v[152:155], v[78:81], v[62:65]
	v_mfma_f32_16x16x32_bf16 v[58:61], v[158:161], v[78:81], v[58:61]
	v_mfma_f32_16x16x32_bf16 v[54:57], v[152:155], v[94:97], v[54:57]
	v_mfma_f32_16x16x32_bf16 v[50:53], v[158:161], v[94:97], v[50:53]
	v_mfma_f32_16x16x32_bf16 v[46:49], v[148:151], v[196:199], v[46:49]
	v_mfma_f32_16x16x32_bf16 v[42:45], v[180:183], v[196:199], v[42:45]
	v_mfma_f32_16x16x32_bf16 v[38:41], v[152:155], v[208:211], v[38:41]
	v_mfma_f32_16x16x32_bf16 v[34:37], v[158:161], v[208:211], v[34:37]
	v_mfma_f32_16x16x32_bf16 v[212:215], v[152:155], v[200:203], v[46:49]
	v_mfma_f32_16x16x32_bf16 v[232:235], v[158:161], v[200:203], v[42:45]
	s_setprio 0
	s_setprio 1
	v_mfma_f32_16x16x32_bf16 v[22:25], v[106:109], v[90:93], v[22:25]
	v_mfma_f32_16x16x32_bf16 v[18:21], v[220:223], v[90:93], v[18:21]
	v_mfma_f32_16x16x32_bf16 v[6:9], v[106:109], v[204:207], v[6:9]
	v_mfma_f32_16x16x32_bf16 v[2:5], v[220:223], v[204:207], v[2:5]
	v_mfma_f32_16x16x32_bf16 v[30:33], v[106:109], v[74:77], v[30:33]
	v_mfma_f32_16x16x32_bf16 v[26:29], v[220:223], v[74:77], v[26:29]
	v_mfma_f32_16x16x32_bf16 v[22:25], v[110:113], v[94:97], v[22:25]
	v_mfma_f32_16x16x32_bf16 v[18:21], v[224:227], v[94:97], v[18:21]
	v_mfma_f32_16x16x32_bf16 v[14:17], v[106:109], v[196:199], v[14:17]
	v_mfma_f32_16x16x32_bf16 v[10:13], v[220:223], v[196:199], v[10:13]
	v_mfma_f32_16x16x32_bf16 v[6:9], v[110:113], v[208:211], v[6:9]
	v_mfma_f32_16x16x32_bf16 v[2:5], v[224:227], v[208:211], v[2:5]
	v_mfma_f32_16x16x32_bf16 v[148:151], v[110:113], v[78:81], v[30:33]
	v_mfma_f32_16x16x32_bf16 v[152:155], v[224:227], v[78:81], v[26:29]
	v_mfma_f32_16x16x32_bf16 v[156:159], v[110:113], v[200:203], v[14:17]
	v_mfma_f32_16x16x32_bf16 v[180:183], v[224:227], v[200:203], v[10:13]
	s_setprio 0
	s_barrier
	s_nop 0
	ds_read_b128 v[10:13], v147
	ds_read_b128 v[14:17], v147 offset:1024
	ds_read_b128 v[196:199], v147 offset:2048
	ds_read_b128 v[200:203], v147 offset:3072
	ds_read_b128 v[26:29], v141 offset:32768
	ds_read_b128 v[30:33], v141 offset:33792
	ds_read_b128 v[42:45], v140 offset:32768
	ds_read_b128 v[46:49], v140 offset:33792
	ds_read_b128 v[204:207], v139 offset:32768
	ds_read_b128 v[208:211], v139 offset:33792
	ds_read_b128 v[220:223], v138 offset:32768
	ds_read_b128 v[224:227], v138 offset:33792
	s_waitcnt vmcnt(2)
	s_barrier
; #define WAIT_V(n) asm volatile("s_waitcnt vmcnt(%0)" ::"n"(n) : "memory")
; #define WAIT_L(n) asm volatile("s_waitcnt lgkmcnt(%0)" ::"n"(n) : "memory")
; #define LDA(dst, b, h) for (int m = 0; m < 4; ++m) for (int k = 0; k < 2; ++k) \
;     dst[m][k] = *reinterpret_cast<const bf16x8*>((char*)SA(b, h) + lds_byte(wr * 64 + m * 16 + fr, k * 32 + fq * 8))
; #define LDB(dst, b, h) for (int n = 0; n < 2; ++n) for (int k = 0; k < 2; ++k) \
;     dst[n][k] = *reinterpret_cast<const bf16x8*>((char*)SB(b, h) + lds_byte(wc * 32 + n * 16 + fr, k * 32 + fq * 8))
; #define MMA(ai, bj, At_, Bt_) do { __builtin_amdgcn_s_setprio(1); \
;     for (int m = 0; m < 4; ++m) for (int n = 0; n < 2; ++n) for (int k = 0; k < 2; ++k) \
;       acc[ai][bj][m][n] = __builtin_amdgcn_mfma_f32_16x16x32_bf16(Bt_[n][k], At_[m][k], acc[ai][bj][m][n], 0, 0, 0); \
;     __builtin_amdgcn_s_setprio(0); } while (0)
; #define BAR __builtin_amdgcn_s_barrier()
; DEVI void gemm_tile(const Params& p, int layer, const u16* __restrict__ A, unsigned lda, const u16* __restrict__ Bt, unsigned ldb, int K,
;                     int brow, int bcol, int ekind, const int tid_) {
;     ...
;   { LDB(B0, 1, 0); LDA(At, 1, 0); WAIT_V(2); BAR; WAIT_L(0); MMA(0, 0, At, B0); BAR;
;     LDB(B1, 1, 1); WAIT_V(0); BAR; WAIT_L(0); MMA(0, 1, At, B1); BAR;
;     LDA(At, 1, 1); BAR; WAIT_L(0); MMA(1, 0, At, B0); MMA(1, 1, At, B1); BAR; }
;   if (wr == 0) BAR;
	s_waitcnt lgkmcnt(0)
	s_setprio 1
	v_mfma_f32_16x16x32_bf16 v[74:77], v[10:13], v[26:29], v[126:129]
	v_mfma_f32_16x16x32_bf16 v[126:129], v[14:17], v[30:33], v[74:77]
	v_mfma_f32_16x16x32_bf16 v[74:77], v[196:199], v[26:29], v[122:125]
	v_mfma_f32_16x16x32_bf16 v[122:125], v[200:203], v[30:33], v[74:77]
	v_mfma_f32_16x16x32_bf16 v[74:77], v[10:13], v[42:45], v[118:121]
	v_mfma_f32_16x16x32_bf16 v[110:113], v[14:17], v[46:49], v[74:77]
	v_mfma_f32_16x16x32_bf16 v[74:77], v[196:199], v[42:45], v[114:117]
	v_mfma_f32_16x16x32_bf16 v[106:109], v[200:203], v[46:49], v[74:77]
	v_mfma_f32_16x16x32_bf16 v[74:77], v[10:13], v[204:207], v[162:165]
	v_mfma_f32_16x16x32_bf16 v[94:97], v[14:17], v[208:211], v[74:77]
	v_mfma_f32_16x16x32_bf16 v[74:77], v[196:199], v[204:207], v[216:219]
	v_mfma_f32_16x16x32_bf16 v[90:93], v[200:203], v[208:211], v[74:77]
	v_mfma_f32_16x16x32_bf16 v[74:77], v[10:13], v[220:223], v[102:105]
	v_mfma_f32_16x16x32_bf16 v[78:81], v[14:17], v[224:227], v[74:77]
	v_mfma_f32_16x16x32_bf16 v[74:77], v[196:199], v[220:223], v[98:101]
	v_mfma_f32_16x16x32_bf16 v[74:77], v[200:203], v[224:227], v[74:77]
	s_setprio 0
	s_barrier
	ds_read_b128 v[160:163], v142
	ds_read_b128 v[164:167], v142 offset:1024
	ds_read_b128 v[216:219], v142 offset:2048
	ds_read_b128 v[142:145], v142 offset:3072
	s_waitcnt vmcnt(0)
	s_barrier
	s_waitcnt lgkmcnt(0)
	s_setprio 1
	v_mfma_f32_16x16x32_bf16 v[98:101], v[160:163], v[26:29], v[228:231]
	v_mfma_f32_16x16x32_bf16 v[26:29], v[216:219], v[26:29], v[184:187]
	v_mfma_f32_16x16x32_bf16 v[114:117], v[142:145], v[30:33], v[26:29]
	v_mfma_f32_16x16x32_bf16 v[26:29], v[160:163], v[42:45], v[86:89]
	v_mfma_f32_16x16x32_bf16 v[102:105], v[164:167], v[46:49], v[26:29]
	v_mfma_f32_16x16x32_bf16 v[26:29], v[216:219], v[42:45], v[82:85]
	v_mfma_f32_16x16x32_bf16 v[118:121], v[164:167], v[30:33], v[98:101]
	v_mfma_f32_16x16x32_bf16 v[98:101], v[142:145], v[46:49], v[26:29]
	v_mfma_f32_16x16x32_bf16 v[26:29], v[160:163], v[204:207], v[188:191]
	v_mfma_f32_16x16x32_bf16 v[86:89], v[164:167], v[208:211], v[26:29]
	v_mfma_f32_16x16x32_bf16 v[26:29], v[216:219], v[204:207], v[192:195]
	v_mfma_f32_16x16x32_bf16 v[82:85], v[142:145], v[208:211], v[26:29]
	v_mfma_f32_16x16x32_bf16 v[26:29], v[160:163], v[220:223], v[70:73]
	v_mfma_f32_16x16x32_bf16 v[70:73], v[164:167], v[224:227], v[26:29]
	v_mfma_f32_16x16x32_bf16 v[26:29], v[216:219], v[220:223], v[66:69]
	v_mfma_f32_16x16x32_bf16 v[66:69], v[142:145], v[224:227], v[26:29]
	s_setprio 0
	s_barrier
	ds_read_b128 v[184:187], v141 offset:49152
	ds_read_b128 v[188:191], v141 offset:50176
	ds_read_b128 v[192:195], v140 offset:49152
	ds_read_b128 v[204:207], v140 offset:50176
	ds_read_b128 v[208:211], v139 offset:49152
	ds_read_b128 v[220:223], v139 offset:50176
	ds_read_b128 v[224:227], v138 offset:49152
	ds_read_b128 v[138:141], v138 offset:50176
	s_barrier
	s_waitcnt lgkmcnt(0)
	s_setprio 1
	v_mfma_f32_16x16x32_bf16 v[26:29], v[10:13], v[184:187], v[62:65]
	v_mfma_f32_16x16x32_bf16 v[62:65], v[14:17], v[188:191], v[26:29]
	v_mfma_f32_16x16x32_bf16 v[26:29], v[196:199], v[184:187], v[58:61]
	v_mfma_f32_16x16x32_bf16 v[58:61], v[200:203], v[188:191], v[26:29]
	v_mfma_f32_16x16x32_bf16 v[26:29], v[10:13], v[192:195], v[54:57]
	v_mfma_f32_16x16x32_bf16 v[46:49], v[14:17], v[204:207], v[26:29]
	v_mfma_f32_16x16x32_bf16 v[26:29], v[196:199], v[192:195], v[50:53]
	v_mfma_f32_16x16x32_bf16 v[42:45], v[200:203], v[204:207], v[26:29]
	v_mfma_f32_16x16x32_bf16 v[26:29], v[10:13], v[208:211], v[212:215]
	v_mfma_f32_16x16x32_bf16 v[10:13], v[10:13], v[224:227], v[38:41]
	v_mfma_f32_16x16x32_bf16 v[30:33], v[14:17], v[220:223], v[26:29]
	v_mfma_f32_16x16x32_bf16 v[26:29], v[196:199], v[208:211], v[232:235]
	v_mfma_f32_16x16x32_bf16 v[14:17], v[14:17], v[138:141], v[10:13]
	v_mfma_f32_16x16x32_bf16 v[10:13], v[196:199], v[224:227], v[34:37]
	v_mfma_f32_16x16x32_bf16 v[26:29], v[200:203], v[220:223], v[26:29]
	v_mfma_f32_16x16x32_bf16 v[10:13], v[200:203], v[138:141], v[10:13]
	s_setprio 0
	s_setprio 1
	v_mfma_f32_16x16x32_bf16 v[34:37], v[160:163], v[184:187], v[148:151]
	v_mfma_f32_16x16x32_bf16 v[54:57], v[164:167], v[188:191], v[34:37]
	v_mfma_f32_16x16x32_bf16 v[34:37], v[216:219], v[184:187], v[152:155]
	v_mfma_f32_16x16x32_bf16 v[18:21], v[216:219], v[192:195], v[18:21]
	v_mfma_f32_16x16x32_bf16 v[50:53], v[142:145], v[188:191], v[34:37]
	v_mfma_f32_16x16x32_bf16 v[22:25], v[160:163], v[192:195], v[22:25]
	v_mfma_f32_16x16x32_bf16 v[34:37], v[142:145], v[204:207], v[18:21]
	v_mfma_f32_16x16x32_bf16 v[18:21], v[160:163], v[208:211], v[156:159]
	v_mfma_f32_16x16x32_bf16 v[38:41], v[164:167], v[204:207], v[22:25]
	v_mfma_f32_16x16x32_bf16 v[22:25], v[164:167], v[220:223], v[18:21]
	v_mfma_f32_16x16x32_bf16 v[18:21], v[216:219], v[208:211], v[180:183]
	v_mfma_f32_16x16x32_bf16 v[6:9], v[160:163], v[224:227], v[6:9]
	v_mfma_f32_16x16x32_bf16 v[2:5], v[216:219], v[224:227], v[2:5]
	v_mfma_f32_16x16x32_bf16 v[18:21], v[142:145], v[220:223], v[18:21]
	v_mfma_f32_16x16x32_bf16 v[6:9], v[164:167], v[138:141], v[6:9]
	v_mfma_f32_16x16x32_bf16 v[2:5], v[142:145], v[138:141], v[2:5]
	s_setprio 0
	s_movk_i32 s2, 0x100
	v_cmp_gt_u32_e32 vcc, s2, v136
	s_barrier
	s_and_saveexec_b64 s[2:3], vcc
	s_cbranch_execz .LBB0_316
	s_barrier
